# st0 x->f16+sumsq row loop: 8 row loads issued up front, next row prefetched per chunk, counted vmcnt
# baseline (speedup 1.0000x reference)
; __device__ __forceinline__ unsigned pkh(float a, float b) { typedef _Float16 h2 __attribute__((ext_vector_type(2))); h2 v; v.x = (f16)a; v.y = (f16)b; return __builtin_bit_cast(unsigned, v); }
; __global__ void __launch_bounds__(512, 2) fwd_megakernel(Params P) {
;     ...
;                     const float* xin = kp->in[I_X];
;                     for (int m = gw; m < M; m += NGW) {
;                         const f32x4* xr = (const f32x4*)(xin + (size_t)m * D) + lane; float ssq = 0.f;
; #pragma unroll
;                         for (int j = 0; j < 8; ++j) { const f32x4 v = __builtin_nontemporal_load(xr + 64 * j); ssq += (v[0] * v[0] + v[1] * v[1]) + (v[2] * v[2] + v[3] * v[3]);
;                             ((unsigned long long*)(XH + (size_t)m * D))[lane + 64 * j] = (unsigned long long)pkh(v[0], v[1]) | ((unsigned long long)pkh(v[2], v[3]) << 32); }
;                         ssq = wave_sum(ssq);
;                         if (lane == 0) RS[m] = ssq;
;                     }
.LBB0_108:
	s_or_b64 exec, exec, s[10:11]
	s_cmpk_gt_i32 s20, 0x7fff
	s_cbranch_scc1 .LBB0_113
	v_and_b32_e32 v1, 64, v236
	v_add_u32_e32 v2, 64, v1
	v_xor_b32_e32 v1, 1, v236
	v_cmp_lt_i32_e32 vcc, v1, v2
	v_xor_b32_e32 v3, 2, v236
	s_ashr_i32 s21, s20, 31
	v_cndmask_b32_e32 v1, v236, v1, vcc
	v_cmp_lt_i32_e32 vcc, v3, v2
	s_lshl_b64 s[10:11], s[20:21], 2
	s_load_dwordx2 s[12:13], s[24:25], 0x0
	s_load_dwordx2 s[14:15], s[24:25], 0xc0
	v_cndmask_b32_e32 v3, v236, v3, vcc
	v_lshlrev_b32_e32 v10, 2, v3
	v_xor_b32_e32 v3, 4, v236
	v_cmp_lt_i32_e32 vcc, v3, v2
	s_waitcnt lgkmcnt(0)
	s_add_u32 s3, s22, s10
	s_addc_u32 s11, s23, s11
	v_cndmask_b32_e32 v3, v236, v3, vcc
	v_lshlrev_b32_e32 v11, 2, v3
	v_xor_b32_e32 v3, 8, v236
	v_cmp_lt_i32_e32 vcc, v3, v2
	s_add_u32 s10, s3, 0x2f90000
	s_addc_u32 s11, s11, 0
	v_cndmask_b32_e32 v3, v236, v3, vcc
	v_lshlrev_b32_e32 v12, 2, v3
	v_xor_b32_e32 v3, 16, v236
	v_cmp_lt_i32_e32 vcc, v3, v2
	s_lshl_b64 s[22:23], s[20:21], 13
	s_add_u32 s12, s12, s22
	v_cndmask_b32_e32 v3, v236, v3, vcc
	v_lshlrev_b32_e32 v13, 2, v3
	v_xor_b32_e32 v3, 32, v236
	v_cmp_lt_i32_e32 vcc, v3, v2
	s_addc_u32 s13, s13, s23
	v_lshlrev_b32_e32 v8, 3, v18
	v_cndmask_b32_e32 v2, v236, v3, vcc
	v_lshlrev_b32_e32 v14, 2, v2
	v_lshlrev_b32_e32 v2, 4, v18
	v_mov_b32_e32 v3, v0
	v_lshl_add_u64 v[2:3], s[12:13], 0, v[2:3]
	s_mov_b64 s[12:13], 0x1c00
	v_lshl_add_u64 v[2:3], v[2:3], 0, s[12:13]
	s_lshl_b64 s[12:13], s[20:21], 12
	s_add_u32 s12, s14, s12
	v_mov_b32_e32 v9, v0
	s_addc_u32 s13, s15, s13
	v_lshlrev_b32_e32 v1, 2, v1
	v_cmp_eq_u32_e64 s[8:9], 0, v18
	v_lshl_add_u64 v[8:9], s[12:13], 0, v[8:9]
	v_add_co_u32_e32 v24, vcc, 0xfffff000, v2
	s_nop 1
	v_addc_co_u32_e32 v25, vcc, -1, v3, vcc
	global_load_dword v84, v[2:3], off
	global_load_dwordx4 v[48:51], v[24:25], off offset:-3072 nt
	global_load_dword v84, v[2:3], off
	global_load_dwordx4 v[52:55], v[24:25], off offset:-2048 nt
	global_load_dword v84, v[2:3], off
	global_load_dwordx4 v[56:59], v[24:25], off offset:-1024 nt
	global_load_dword v84, v[2:3], off
	global_load_dwordx4 v[60:63], v[2:3], off offset:-4096 nt
	global_load_dword v84, v[2:3], off
	global_load_dwordx4 v[64:67], v[2:3], off offset:-3072 nt
	global_load_dword v84, v[2:3], off
	global_load_dwordx4 v[68:71], v[2:3], off offset:-2048 nt
	global_load_dword v84, v[2:3], off
	global_load_dwordx4 v[72:75], v[2:3], off offset:-1024 nt
	global_load_dword v84, v[2:3], off
	global_load_dwordx4 v[76:79], v[2:3], off nt
	global_load_dword v84, v[2:3], off
	s_branch .LBB0_111

; __device__ __forceinline__ unsigned pkh(float a, float b) { typedef _Float16 h2 __attribute__((ext_vector_type(2))); h2 v; v.x = (f16)a; v.y = (f16)b; return __builtin_bit_cast(unsigned, v); }
; __global__ void __launch_bounds__(512, 2) fwd_megakernel(Params P) {
;     ...
;                     for (int m = gw; m < M; m += NGW) {
;                         const f32x4* xr = (const f32x4*)(xin + (size_t)m * D) + lane; float ssq = 0.f;
; #pragma unroll
;                         for (int j = 0; j < 8; ++j) { const f32x4 v = __builtin_nontemporal_load(xr + 64 * j); ssq += (v[0] * v[0] + v[1] * v[1]) + (v[2] * v[2] + v[3] * v[3]);
;                             ((unsigned long long*)(XH + (size_t)m * D))[lane + 64 * j] = (unsigned long long)pkh(v[0], v[1]) | ((unsigned long long)pkh(v[2], v[3]) << 32); }
;                         ssq = wave_sum(ssq);
;                         if (lane == 0) RS[m] = ssq;
.LBB0_111:
	s_add_i32 s14, s20, s38
	s_cmpk_gt_i32 s14, 0x7fff
	s_cselect_b32 s22, 0, s74
	s_cselect_b32 s23, 0, s75
	v_lshl_add_u64 v[80:81], v[2:3], 0, s[22:23]
	s_waitcnt lgkmcnt(0)
	v_add_co_u32_e32 v82, vcc, 0xfffff000, v80
	s_nop 1
	v_addc_co_u32_e32 v83, vcc, -1, v81, vcc
	s_waitcnt vmcnt(15)
	v_cvt_pk_f16_f32 v20, v48, v49
	v_cvt_pk_f16_f32 v21, v50, v51
	global_store_dwordx2 v[8:9], v[20:21], off
	v_mul_f32_e32 v15, v49, v49
	v_mul_f32_e32 v17, v51, v51
	v_fmac_f32_e32 v15, v48, v48
	v_fmac_f32_e32 v17, v50, v50
	v_add_f32_e32 v15, v15, v17
	global_load_dwordx4 v[48:51], v[82:83], off offset:-3072 nt
	s_waitcnt vmcnt(15)
	v_cvt_pk_f16_f32 v22, v52, v53
	v_cvt_pk_f16_f32 v23, v54, v55
	global_store_dwordx2 v[8:9], v[22:23], off offset:512
	v_mul_f32_e32 v16, v53, v53
	v_mul_f32_e32 v17, v55, v55
	v_fmac_f32_e32 v16, v52, v52
	v_fmac_f32_e32 v17, v54, v54
	v_add_f32_e32 v16, v16, v17
	v_add_f32_e32 v15, v15, v16
	global_load_dwordx4 v[52:55], v[82:83], off offset:-2048 nt
	s_waitcnt vmcnt(15)
	v_cvt_pk_f16_f32 v24, v56, v57
	v_cvt_pk_f16_f32 v25, v58, v59
	global_store_dwordx2 v[8:9], v[24:25], off offset:1024
	v_mul_f32_e32 v16, v57, v57
	v_mul_f32_e32 v17, v59, v59
	v_fmac_f32_e32 v16, v56, v56
	v_fmac_f32_e32 v17, v58, v58
	v_add_f32_e32 v16, v16, v17
	v_add_f32_e32 v15, v15, v16
	global_load_dwordx4 v[56:59], v[82:83], off offset:-1024 nt
	s_waitcnt vmcnt(15)
	v_cvt_pk_f16_f32 v26, v60, v61
	v_cvt_pk_f16_f32 v27, v62, v63
	global_store_dwordx2 v[8:9], v[26:27], off offset:1536
	v_mul_f32_e32 v16, v61, v61
	v_mul_f32_e32 v17, v63, v63
	v_fmac_f32_e32 v16, v60, v60
	v_fmac_f32_e32 v17, v62, v62
	v_add_f32_e32 v16, v16, v17
	v_add_f32_e32 v15, v15, v16
	global_load_dwordx4 v[60:63], v[80:81], off offset:-4096 nt
	s_waitcnt vmcnt(15)
	v_cvt_pk_f16_f32 v28, v64, v65
	v_cvt_pk_f16_f32 v29, v66, v67
	global_store_dwordx2 v[8:9], v[28:29], off offset:2048
	v_mul_f32_e32 v16, v65, v65
	v_mul_f32_e32 v17, v67, v67
	v_fmac_f32_e32 v16, v64, v64
	v_fmac_f32_e32 v17, v66, v66
	v_add_f32_e32 v16, v16, v17
	v_add_f32_e32 v15, v15, v16
	global_load_dwordx4 v[64:67], v[80:81], off offset:-3072 nt
	s_waitcnt vmcnt(15)
	v_cvt_pk_f16_f32 v30, v68, v69
	v_cvt_pk_f16_f32 v31, v70, v71
	global_store_dwordx2 v[8:9], v[30:31], off offset:2560
	v_mul_f32_e32 v16, v69, v69
	v_mul_f32_e32 v17, v71, v71
	v_fmac_f32_e32 v16, v68, v68
	v_fmac_f32_e32 v17, v70, v70
	v_add_f32_e32 v16, v16, v17
	v_add_f32_e32 v15, v15, v16
	global_load_dwordx4 v[68:71], v[80:81], off offset:-2048 nt
	s_waitcnt vmcnt(15)
	v_cvt_pk_f16_f32 v32, v72, v73
	v_cvt_pk_f16_f32 v33, v74, v75
	global_store_dwordx2 v[8:9], v[32:33], off offset:3072
	v_mul_f32_e32 v16, v73, v73
	v_mul_f32_e32 v17, v75, v75
	v_fmac_f32_e32 v16, v72, v72
	v_fmac_f32_e32 v17, v74, v74
	v_add_f32_e32 v16, v16, v17
	v_add_f32_e32 v15, v15, v16
	global_load_dwordx4 v[72:75], v[80:81], off offset:-1024 nt
	s_waitcnt vmcnt(15)
	v_cvt_pk_f16_f32 v34, v76, v77
	v_cvt_pk_f16_f32 v35, v78, v79
	global_store_dwordx2 v[8:9], v[34:35], off offset:3584
	v_mul_f32_e32 v16, v77, v77
	v_mul_f32_e32 v17, v79, v79
	v_fmac_f32_e32 v16, v76, v76
	v_fmac_f32_e32 v17, v78, v78
	v_add_f32_e32 v16, v16, v17
	v_add_f32_e32 v15, v15, v16
	global_load_dwordx4 v[76:79], v[80:81], off nt
	ds_bpermute_b32 v16, v1, v15
	s_waitcnt lgkmcnt(0)
	v_add_f32_e32 v15, v15, v16
	ds_bpermute_b32 v16, v10, v15
	s_waitcnt lgkmcnt(0)
	v_add_f32_e32 v15, v15, v16
	ds_bpermute_b32 v16, v11, v15
	s_waitcnt lgkmcnt(0)
	v_add_f32_e32 v15, v15, v16
	ds_bpermute_b32 v16, v12, v15
	s_waitcnt lgkmcnt(0)
	v_add_f32_e32 v15, v15, v16
	ds_bpermute_b32 v16, v13, v15
	s_waitcnt lgkmcnt(0)
	v_add_f32_e32 v15, v15, v16
	ds_bpermute_b32 v16, v14, v15
	s_and_saveexec_b64 s[12:13], s[8:9]
	s_cbranch_execz .LBB0_110
	s_waitcnt lgkmcnt(0)
	v_add_f32_e32 v15, v15, v16
	global_store_dword v0, v15, s[10:11]
	s_branch .LBB0_110
.Lst0x_drain:
	s_waitcnt vmcnt(0)
.LBB0_113:
	s_andn2_b64 vcc, exec, s[18:19]
	s_mov_b32 s53, 1
	s_cbranch_vccnz .LBB0_137
	s_mov_b64 s[8:9], -1
	s_cmp_lg_u32 s52, 1
	s_mov_b64 s[6:7], -1
	s_cbranch_scc0 .LBB0_138
	s_and_b64 vcc, exec, s[16:17]
	s_cbranch_vccz .LBB0_296
	s_cmp_lt_i32 s52, 6
	s_cbranch_scc1 .LBB0_297
	s_cmp_lt_i32 s52, 7
	s_cbranch_scc1 .LBB0_134
	s_mov_b64 s[8:9], -1
	s_cmp_lt_i32 s52, 8
	s_cbranch_scc1 .LBB0_122
	s_cmp_lg_u32 s52, 8
	s_mov_b32 s53, 2
	s_cbranch_scc0 .LBB0_121
	s_mov_b32 s53, 1
